# scanner: after the chunk barrier step 0 is read alone, steps 1 and 2 together one slot later
# baseline (speedup 1.0000x reference)
.LBB0_787:
	s_and_saveexec_b64 s[0:1], s[8:9]
	s_xor_b64 s[36:37], exec, s[0:1]
	s_cbranch_execz .LBB0_791
	s_and_saveexec_b64 s[44:45], s[26:27]
	s_cbranch_execz .LBB0_790
	s_and_b32 s0, s54, 1
	s_mul_i32 s1, s0, 0xc000
	s_lshl_b32 s4, s30, 2
	v_add_u32_e32 v10, s1, v97
	s_add_i32 s1, s1, s4
	v_lshl_add_u32 v11, v95, 2, s1
	v_lshl_add_u32 v12, s0, 14, v102
	v_pk_fma_f32 v[4:5], v[60:61], v[64:65], v[56:57] op_sel_hi:[0,1,1]
	v_pk_fma_f32 v[6:7], v[60:61], v[66:67], v[58:59] op_sel_hi:[0,1,1]
	v_pk_mul_f32 v[80:81], v[4:5], v[80:81]
	v_pk_fma_f32 v[80:81], v[6:7], v[82:83], v[80:81]
	v_add_f32_e32 v80, v80, v81
	v_pk_mul_f32 v[76:77], v[76:77], v[2:3] op_sel_hi:[1,0]
	v_pk_mul_f32 v[78:79], v[78:79], v[2:3] op_sel_hi:[1,0]
	v_add_f32_dpp v80, v80, v80 quad_perm:[1,0,3,2] row_mask:0xf bank_mask:0xf bound_ctrl:1
	v_pk_fma_f32 v[76:77], v[4:5], v[68:69], v[76:77]
	v_pk_fma_f32 v[78:79], v[6:7], v[70:71], v[78:79]
	v_add_f32_dpp v80, v80, v80 quad_perm:[2,3,0,1] row_mask:0xf bank_mask:0xf bound_ctrl:1
	v_pk_mul_f32 v[52:53], v[52:53], v[4:5]
	v_pk_fma_f32 v[52:53], v[6:7], v[54:55], v[52:53]
	v_add_f32_dpp v80, v80, v80 row_half_mirror row_mask:0xf bank_mask:0xf bound_ctrl:1
	v_add_f32_e32 v9, v52, v53
	ds_read_b128 v[36:39], v10 offset:512
	ds_read2st64_b32 v[0:1], v11 offset0:5 offset1:11
	ds_read_b128 v[40:43], v10 offset:768
	ds_read_b128 v[28:31], v10 offset:0
	ds_read_b128 v[44:47], v10 offset:1024
	ds_read_b128 v[32:35], v10 offset:256
	v_add_f32_dpp v80, v80, v80 row_mirror row_mask:0xf bank_mask:0xf bound_ctrl:1
	v_pk_fma_f32 v[4:5], v[80:81], v[84:85], v[76:77] op_sel_hi:[0,1,1]
	v_pk_fma_f32 v[6:7], v[80:81], v[86:87], v[78:79] op_sel_hi:[0,1,1]
	v_pk_mul_f32 v[116:117], v[4:5], v[116:117]
	v_pk_fma_f32 v[116:117], v[6:7], v[118:119], v[116:117]
	v_add_f32_e32 v116, v116, v117
	v_pk_mul_f32 v[112:113], v[112:113], v[2:3] op_sel:[0,1] op_sel_hi:[1,1]
	v_pk_mul_f32 v[114:115], v[114:115], v[2:3] op_sel:[0,1] op_sel_hi:[1,1]
	v_add_f32_dpp v116, v116, v116 quad_perm:[1,0,3,2] row_mask:0xf bank_mask:0xf bound_ctrl:1
	v_pk_fma_f32 v[112:113], v[4:5], v[104:105], v[112:113]
	v_pk_fma_f32 v[114:115], v[6:7], v[106:107], v[114:115]
	v_add_f32_dpp v116, v116, v116 quad_perm:[2,3,0,1] row_mask:0xf bank_mask:0xf bound_ctrl:1
	v_pk_mul_f32 v[72:73], v[72:73], v[4:5]
	v_pk_fma_f32 v[72:73], v[6:7], v[74:75], v[72:73]
	v_add_f32_dpp v116, v116, v116 row_half_mirror row_mask:0xf bank_mask:0xf bound_ctrl:1
	v_add_f32_e32 v8, v72, v73
	ds_read_b128 v[56:59], v10 offset:2048
	ds_read_b128 v[60:63], v10 offset:2304
	ds_read_b128 v[48:51], v10 offset:1536
	ds_read_b128 v[64:67], v10 offset:2560
	ds_read_b128 v[52:55], v10 offset:1792
	ds_read_b128 v[76:79], v10 offset:3584
	ds_read2st64_b32 v[2:3], v11 offset0:17 offset1:23
	ds_read_b128 v[80:83], v10 offset:3840
	ds_read_b128 v[68:71], v10 offset:3072
	ds_read_b128 v[84:87], v10 offset:4096
	ds_read_b128 v[72:75], v10 offset:3328
	ds_write2st64_b32 v12, v9, v8 offset0:0 offset1:2
	v_add_f32_dpp v116, v116, v116 row_mirror row_mask:0xf bank_mask:0xf bound_ctrl:1
	v_pk_fma_f32 v[4:5], v[116:117], v[120:121], v[112:113] op_sel_hi:[0,1,1]
	v_pk_fma_f32 v[6:7], v[116:117], v[122:123], v[114:115] op_sel_hi:[0,1,1]
	s_waitcnt lgkmcnt(12)
	v_pk_mul_f32 v[40:41], v[4:5], v[40:41]
	v_pk_fma_f32 v[40:41], v[6:7], v[42:43], v[40:41]
	v_add_f32_e32 v40, v40, v41
	v_pk_mul_f32 v[36:37], v[36:37], v[0:1] op_sel_hi:[1,0]
	v_pk_mul_f32 v[38:39], v[38:39], v[0:1] op_sel_hi:[1,0]
	v_add_f32_dpp v40, v40, v40 quad_perm:[1,0,3,2] row_mask:0xf bank_mask:0xf bound_ctrl:1
	v_pk_fma_f32 v[36:37], v[4:5], v[28:29], v[36:37]
	v_pk_fma_f32 v[38:39], v[6:7], v[30:31], v[38:39]
	v_add_f32_dpp v40, v40, v40 quad_perm:[2,3,0,1] row_mask:0xf bank_mask:0xf bound_ctrl:1
	v_pk_mul_f32 v[108:109], v[108:109], v[4:5]
	v_pk_fma_f32 v[108:109], v[6:7], v[110:111], v[108:109]
	v_add_f32_dpp v40, v40, v40 row_half_mirror row_mask:0xf bank_mask:0xf bound_ctrl:1
	v_add_f32_e32 v9, v108, v109
	ds_read_b128 v[112:115], v10 offset:5120
	ds_read_b128 v[116:119], v10 offset:5376
	ds_read_b128 v[104:107], v10 offset:4608
	ds_read_b128 v[120:123], v10 offset:5632
	ds_read_b128 v[108:111], v10 offset:4864
	v_add_f32_dpp v40, v40, v40 row_mirror row_mask:0xf bank_mask:0xf bound_ctrl:1
	v_pk_fma_f32 v[4:5], v[40:41], v[44:45], v[36:37] op_sel_hi:[0,1,1]
	v_pk_fma_f32 v[6:7], v[40:41], v[46:47], v[38:39] op_sel_hi:[0,1,1]
	s_waitcnt lgkmcnt(12)
	v_pk_mul_f32 v[60:61], v[4:5], v[60:61]
	v_pk_fma_f32 v[60:61], v[6:7], v[62:63], v[60:61]
	v_add_f32_e32 v60, v60, v61
	v_pk_mul_f32 v[56:57], v[56:57], v[0:1] op_sel:[0,1] op_sel_hi:[1,1]
	v_pk_mul_f32 v[58:59], v[58:59], v[0:1] op_sel:[0,1] op_sel_hi:[1,1]
	v_add_f32_dpp v60, v60, v60 quad_perm:[1,0,3,2] row_mask:0xf bank_mask:0xf bound_ctrl:1
	v_pk_fma_f32 v[56:57], v[4:5], v[48:49], v[56:57]
	v_pk_fma_f32 v[58:59], v[6:7], v[50:51], v[58:59]
	v_add_f32_dpp v60, v60, v60 quad_perm:[2,3,0,1] row_mask:0xf bank_mask:0xf bound_ctrl:1
	v_pk_mul_f32 v[32:33], v[32:33], v[4:5]
	v_pk_fma_f32 v[32:33], v[6:7], v[34:35], v[32:33]
	v_add_f32_dpp v60, v60, v60 row_half_mirror row_mask:0xf bank_mask:0xf bound_ctrl:1
	v_add_f32_e32 v8, v32, v33
	ds_read_b128 v[36:39], v10 offset:6656
	ds_read2st64_b32 v[0:1], v11 offset0:29 offset1:35
	ds_read_b128 v[40:43], v10 offset:6912
	ds_read_b128 v[28:31], v10 offset:6144
	ds_read_b128 v[44:47], v10 offset:7168
	ds_read_b128 v[32:35], v10 offset:6400
	ds_write2st64_b32 v12, v9, v8 offset0:4 offset1:6
	v_add_f32_dpp v60, v60, v60 row_mirror row_mask:0xf bank_mask:0xf bound_ctrl:1
	v_pk_fma_f32 v[4:5], v[60:61], v[64:65], v[56:57] op_sel_hi:[0,1,1]
	v_pk_fma_f32 v[6:7], v[60:61], v[66:67], v[58:59] op_sel_hi:[0,1,1]
	s_waitcnt lgkmcnt(13)
	v_pk_mul_f32 v[80:81], v[4:5], v[80:81]
	v_pk_fma_f32 v[80:81], v[6:7], v[82:83], v[80:81]
	v_add_f32_e32 v80, v80, v81
	v_pk_mul_f32 v[76:77], v[76:77], v[2:3] op_sel_hi:[1,0]
	v_pk_mul_f32 v[78:79], v[78:79], v[2:3] op_sel_hi:[1,0]
	v_add_f32_dpp v80, v80, v80 quad_perm:[1,0,3,2] row_mask:0xf bank_mask:0xf bound_ctrl:1
	v_pk_fma_f32 v[76:77], v[4:5], v[68:69], v[76:77]
	v_pk_fma_f32 v[78:79], v[6:7], v[70:71], v[78:79]
	v_add_f32_dpp v80, v80, v80 quad_perm:[2,3,0,1] row_mask:0xf bank_mask:0xf bound_ctrl:1
	v_pk_mul_f32 v[52:53], v[52:53], v[4:5]
	v_pk_fma_f32 v[52:53], v[6:7], v[54:55], v[52:53]
	v_add_f32_dpp v80, v80, v80 row_half_mirror row_mask:0xf bank_mask:0xf bound_ctrl:1
	v_add_f32_e32 v9, v52, v53
	ds_read_b128 v[56:59], v10 offset:8192
	ds_read_b128 v[60:63], v10 offset:8448
	ds_read_b128 v[48:51], v10 offset:7680
	ds_read_b128 v[64:67], v10 offset:8704
	ds_read_b128 v[52:55], v10 offset:7936
	v_add_f32_dpp v80, v80, v80 row_mirror row_mask:0xf bank_mask:0xf bound_ctrl:1
	v_pk_fma_f32 v[4:5], v[80:81], v[84:85], v[76:77] op_sel_hi:[0,1,1]
	v_pk_fma_f32 v[6:7], v[80:81], v[86:87], v[78:79] op_sel_hi:[0,1,1]
	s_waitcnt lgkmcnt(12)
	v_pk_mul_f32 v[116:117], v[4:5], v[116:117]
	v_pk_fma_f32 v[116:117], v[6:7], v[118:119], v[116:117]
	v_add_f32_e32 v116, v116, v117
	v_pk_mul_f32 v[112:113], v[112:113], v[2:3] op_sel:[0,1] op_sel_hi:[1,1]
	v_pk_mul_f32 v[114:115], v[114:115], v[2:3] op_sel:[0,1] op_sel_hi:[1,1]
	v_add_f32_dpp v116, v116, v116 quad_perm:[1,0,3,2] row_mask:0xf bank_mask:0xf bound_ctrl:1
	v_pk_fma_f32 v[112:113], v[4:5], v[104:105], v[112:113]
	v_pk_fma_f32 v[114:115], v[6:7], v[106:107], v[114:115]
	v_add_f32_dpp v116, v116, v116 quad_perm:[2,3,0,1] row_mask:0xf bank_mask:0xf bound_ctrl:1
	v_pk_mul_f32 v[72:73], v[72:73], v[4:5]
	v_pk_fma_f32 v[72:73], v[6:7], v[74:75], v[72:73]
	v_add_f32_dpp v116, v116, v116 row_half_mirror row_mask:0xf bank_mask:0xf bound_ctrl:1
	v_add_f32_e32 v8, v72, v73
	ds_read_b128 v[76:79], v10 offset:9728
	ds_read2st64_b32 v[2:3], v11 offset0:41 offset1:47
	ds_read_b128 v[80:83], v10 offset:9984
	ds_read_b128 v[68:71], v10 offset:9216
	ds_read_b128 v[84:87], v10 offset:10240
	ds_read_b128 v[72:75], v10 offset:9472
	ds_write2st64_b32 v12, v9, v8 offset0:8 offset1:10
	v_add_f32_dpp v116, v116, v116 row_mirror row_mask:0xf bank_mask:0xf bound_ctrl:1
	v_pk_fma_f32 v[4:5], v[116:117], v[120:121], v[112:113] op_sel_hi:[0,1,1]
	v_pk_fma_f32 v[6:7], v[116:117], v[122:123], v[114:115] op_sel_hi:[0,1,1]
	s_waitcnt lgkmcnt(13)
	v_pk_mul_f32 v[40:41], v[4:5], v[40:41]
	v_pk_fma_f32 v[40:41], v[6:7], v[42:43], v[40:41]
	v_add_f32_e32 v40, v40, v41
	v_pk_mul_f32 v[36:37], v[36:37], v[0:1] op_sel_hi:[1,0]
	v_pk_mul_f32 v[38:39], v[38:39], v[0:1] op_sel_hi:[1,0]
	v_add_f32_dpp v40, v40, v40 quad_perm:[1,0,3,2] row_mask:0xf bank_mask:0xf bound_ctrl:1
	v_pk_fma_f32 v[36:37], v[4:5], v[28:29], v[36:37]
	v_pk_fma_f32 v[38:39], v[6:7], v[30:31], v[38:39]
	v_add_f32_dpp v40, v40, v40 quad_perm:[2,3,0,1] row_mask:0xf bank_mask:0xf bound_ctrl:1
	v_pk_mul_f32 v[108:109], v[108:109], v[4:5]
	v_pk_fma_f32 v[108:109], v[6:7], v[110:111], v[108:109]
	v_add_f32_dpp v40, v40, v40 row_half_mirror row_mask:0xf bank_mask:0xf bound_ctrl:1
	v_add_f32_e32 v9, v108, v109
	ds_read_b128 v[112:115], v10 offset:11264
	ds_read_b128 v[116:119], v10 offset:11520
	ds_read_b128 v[104:107], v10 offset:10752
	ds_read_b128 v[120:123], v10 offset:11776
	ds_read_b128 v[108:111], v10 offset:11008
	v_add_f32_dpp v40, v40, v40 row_mirror row_mask:0xf bank_mask:0xf bound_ctrl:1
	v_pk_fma_f32 v[4:5], v[40:41], v[44:45], v[36:37] op_sel_hi:[0,1,1]
	v_pk_fma_f32 v[6:7], v[40:41], v[46:47], v[38:39] op_sel_hi:[0,1,1]
	s_waitcnt lgkmcnt(12)
	v_pk_mul_f32 v[60:61], v[4:5], v[60:61]
	v_pk_fma_f32 v[60:61], v[6:7], v[62:63], v[60:61]
	v_add_f32_e32 v60, v60, v61
	v_pk_mul_f32 v[56:57], v[56:57], v[0:1] op_sel:[0,1] op_sel_hi:[1,1]
	v_pk_mul_f32 v[58:59], v[58:59], v[0:1] op_sel:[0,1] op_sel_hi:[1,1]
	v_add_f32_dpp v60, v60, v60 quad_perm:[1,0,3,2] row_mask:0xf bank_mask:0xf bound_ctrl:1
	v_pk_fma_f32 v[56:57], v[4:5], v[48:49], v[56:57]
	v_pk_fma_f32 v[58:59], v[6:7], v[50:51], v[58:59]
	v_add_f32_dpp v60, v60, v60 quad_perm:[2,3,0,1] row_mask:0xf bank_mask:0xf bound_ctrl:1
	v_pk_mul_f32 v[32:33], v[32:33], v[4:5]
	v_pk_fma_f32 v[32:33], v[6:7], v[34:35], v[32:33]
	v_add_f32_dpp v60, v60, v60 row_half_mirror row_mask:0xf bank_mask:0xf bound_ctrl:1
	v_add_f32_e32 v8, v32, v33
	ds_read_b128 v[36:39], v10 offset:12800
	ds_read2st64_b32 v[0:1], v11 offset0:53 offset1:59
	ds_read_b128 v[40:43], v10 offset:13056
	ds_read_b128 v[28:31], v10 offset:12288
	ds_read_b128 v[44:47], v10 offset:13312
	ds_read_b128 v[32:35], v10 offset:12544
	ds_write2st64_b32 v12, v9, v8 offset0:12 offset1:14
	v_add_f32_dpp v60, v60, v60 row_mirror row_mask:0xf bank_mask:0xf bound_ctrl:1
	v_pk_fma_f32 v[4:5], v[60:61], v[64:65], v[56:57] op_sel_hi:[0,1,1]
	v_pk_fma_f32 v[6:7], v[60:61], v[66:67], v[58:59] op_sel_hi:[0,1,1]
	s_waitcnt lgkmcnt(13)
	v_pk_mul_f32 v[80:81], v[4:5], v[80:81]
	v_pk_fma_f32 v[80:81], v[6:7], v[82:83], v[80:81]
	v_add_f32_e32 v80, v80, v81
	v_pk_mul_f32 v[76:77], v[76:77], v[2:3] op_sel_hi:[1,0]
	v_pk_mul_f32 v[78:79], v[78:79], v[2:3] op_sel_hi:[1,0]
	v_add_f32_dpp v80, v80, v80 quad_perm:[1,0,3,2] row_mask:0xf bank_mask:0xf bound_ctrl:1
	v_pk_fma_f32 v[76:77], v[4:5], v[68:69], v[76:77]
	v_pk_fma_f32 v[78:79], v[6:7], v[70:71], v[78:79]
	v_add_f32_dpp v80, v80, v80 quad_perm:[2,3,0,1] row_mask:0xf bank_mask:0xf bound_ctrl:1
	v_pk_mul_f32 v[52:53], v[52:53], v[4:5]
	v_pk_fma_f32 v[52:53], v[6:7], v[54:55], v[52:53]
	v_add_f32_dpp v80, v80, v80 row_half_mirror row_mask:0xf bank_mask:0xf bound_ctrl:1
	v_add_f32_e32 v9, v52, v53
	ds_read_b128 v[56:59], v10 offset:14336
	ds_read_b128 v[60:63], v10 offset:14592
	ds_read_b128 v[48:51], v10 offset:13824
	ds_read_b128 v[64:67], v10 offset:14848
	ds_read_b128 v[52:55], v10 offset:14080
	v_add_f32_dpp v80, v80, v80 row_mirror row_mask:0xf bank_mask:0xf bound_ctrl:1
	v_pk_fma_f32 v[4:5], v[80:81], v[84:85], v[76:77] op_sel_hi:[0,1,1]
	v_pk_fma_f32 v[6:7], v[80:81], v[86:87], v[78:79] op_sel_hi:[0,1,1]
	s_waitcnt lgkmcnt(12)
	v_pk_mul_f32 v[116:117], v[4:5], v[116:117]
	v_pk_fma_f32 v[116:117], v[6:7], v[118:119], v[116:117]
	v_add_f32_e32 v116, v116, v117
	v_pk_mul_f32 v[112:113], v[112:113], v[2:3] op_sel:[0,1] op_sel_hi:[1,1]
	v_pk_mul_f32 v[114:115], v[114:115], v[2:3] op_sel:[0,1] op_sel_hi:[1,1]
	v_add_f32_dpp v116, v116, v116 quad_perm:[1,0,3,2] row_mask:0xf bank_mask:0xf bound_ctrl:1
	v_pk_fma_f32 v[112:113], v[4:5], v[104:105], v[112:113]
	v_pk_fma_f32 v[114:115], v[6:7], v[106:107], v[114:115]
	v_add_f32_dpp v116, v116, v116 quad_perm:[2,3,0,1] row_mask:0xf bank_mask:0xf bound_ctrl:1
	v_pk_mul_f32 v[72:73], v[72:73], v[4:5]
	v_pk_fma_f32 v[72:73], v[6:7], v[74:75], v[72:73]
	v_add_f32_dpp v116, v116, v116 row_half_mirror row_mask:0xf bank_mask:0xf bound_ctrl:1
	v_add_f32_e32 v8, v72, v73
	ds_read_b128 v[76:79], v10 offset:15872
	ds_read2st64_b32 v[2:3], v11 offset0:65 offset1:71
	ds_read_b128 v[80:83], v10 offset:16128
	ds_read_b128 v[68:71], v10 offset:15360
	ds_read_b128 v[84:87], v10 offset:16384
	ds_read_b128 v[72:75], v10 offset:15616
	ds_write2st64_b32 v12, v9, v8 offset0:16 offset1:18
	v_add_f32_dpp v116, v116, v116 row_mirror row_mask:0xf bank_mask:0xf bound_ctrl:1
	v_pk_fma_f32 v[4:5], v[116:117], v[120:121], v[112:113] op_sel_hi:[0,1,1]
	v_pk_fma_f32 v[6:7], v[116:117], v[122:123], v[114:115] op_sel_hi:[0,1,1]
	s_waitcnt lgkmcnt(13)
	v_pk_mul_f32 v[40:41], v[4:5], v[40:41]
	v_pk_fma_f32 v[40:41], v[6:7], v[42:43], v[40:41]
	v_add_f32_e32 v40, v40, v41
	v_pk_mul_f32 v[36:37], v[36:37], v[0:1] op_sel_hi:[1,0]
	v_pk_mul_f32 v[38:39], v[38:39], v[0:1] op_sel_hi:[1,0]
	v_add_f32_dpp v40, v40, v40 quad_perm:[1,0,3,2] row_mask:0xf bank_mask:0xf bound_ctrl:1
	v_pk_fma_f32 v[36:37], v[4:5], v[28:29], v[36:37]
	v_pk_fma_f32 v[38:39], v[6:7], v[30:31], v[38:39]
	v_add_f32_dpp v40, v40, v40 quad_perm:[2,3,0,1] row_mask:0xf bank_mask:0xf bound_ctrl:1
	v_pk_mul_f32 v[108:109], v[108:109], v[4:5]
	v_pk_fma_f32 v[108:109], v[6:7], v[110:111], v[108:109]
	v_add_f32_dpp v40, v40, v40 row_half_mirror row_mask:0xf bank_mask:0xf bound_ctrl:1
	v_add_f32_e32 v9, v108, v109
	ds_read_b128 v[112:115], v10 offset:17408
	ds_read_b128 v[116:119], v10 offset:17664
	ds_read_b128 v[104:107], v10 offset:16896
	ds_read_b128 v[120:123], v10 offset:17920
	ds_read_b128 v[108:111], v10 offset:17152
	v_add_f32_dpp v40, v40, v40 row_mirror row_mask:0xf bank_mask:0xf bound_ctrl:1
	v_pk_fma_f32 v[4:5], v[40:41], v[44:45], v[36:37] op_sel_hi:[0,1,1]
	v_pk_fma_f32 v[6:7], v[40:41], v[46:47], v[38:39] op_sel_hi:[0,1,1]
	s_waitcnt lgkmcnt(12)
	v_pk_mul_f32 v[60:61], v[4:5], v[60:61]
	v_pk_fma_f32 v[60:61], v[6:7], v[62:63], v[60:61]
	v_add_f32_e32 v60, v60, v61
	v_pk_mul_f32 v[56:57], v[56:57], v[0:1] op_sel:[0,1] op_sel_hi:[1,1]
	v_pk_mul_f32 v[58:59], v[58:59], v[0:1] op_sel:[0,1] op_sel_hi:[1,1]
	v_add_f32_dpp v60, v60, v60 quad_perm:[1,0,3,2] row_mask:0xf bank_mask:0xf bound_ctrl:1
	v_pk_fma_f32 v[56:57], v[4:5], v[48:49], v[56:57]
	v_pk_fma_f32 v[58:59], v[6:7], v[50:51], v[58:59]
	v_add_f32_dpp v60, v60, v60 quad_perm:[2,3,0,1] row_mask:0xf bank_mask:0xf bound_ctrl:1
	v_pk_mul_f32 v[32:33], v[32:33], v[4:5]
	v_pk_fma_f32 v[32:33], v[6:7], v[34:35], v[32:33]
	v_add_f32_dpp v60, v60, v60 row_half_mirror row_mask:0xf bank_mask:0xf bound_ctrl:1
	v_add_f32_e32 v8, v32, v33
	ds_read_b128 v[36:39], v10 offset:18944
	ds_read2st64_b32 v[0:1], v11 offset0:77 offset1:83
	ds_read_b128 v[40:43], v10 offset:19200
	ds_read_b128 v[28:31], v10 offset:18432
	ds_read_b128 v[44:47], v10 offset:19456
	ds_read_b128 v[32:35], v10 offset:18688
	ds_write2st64_b32 v12, v9, v8 offset0:20 offset1:22
	v_add_f32_dpp v60, v60, v60 row_mirror row_mask:0xf bank_mask:0xf bound_ctrl:1
	v_pk_fma_f32 v[4:5], v[60:61], v[64:65], v[56:57] op_sel_hi:[0,1,1]
	v_pk_fma_f32 v[6:7], v[60:61], v[66:67], v[58:59] op_sel_hi:[0,1,1]
	s_waitcnt lgkmcnt(13)
	v_pk_mul_f32 v[80:81], v[4:5], v[80:81]
	v_pk_fma_f32 v[80:81], v[6:7], v[82:83], v[80:81]
	v_add_f32_e32 v80, v80, v81
	v_pk_mul_f32 v[76:77], v[76:77], v[2:3] op_sel_hi:[1,0]
	v_pk_mul_f32 v[78:79], v[78:79], v[2:3] op_sel_hi:[1,0]
	v_add_f32_dpp v80, v80, v80 quad_perm:[1,0,3,2] row_mask:0xf bank_mask:0xf bound_ctrl:1
	v_pk_fma_f32 v[76:77], v[4:5], v[68:69], v[76:77]
	v_pk_fma_f32 v[78:79], v[6:7], v[70:71], v[78:79]
	v_add_f32_dpp v80, v80, v80 quad_perm:[2,3,0,1] row_mask:0xf bank_mask:0xf bound_ctrl:1
	v_pk_mul_f32 v[52:53], v[52:53], v[4:5]
	v_pk_fma_f32 v[52:53], v[6:7], v[54:55], v[52:53]
	v_add_f32_dpp v80, v80, v80 row_half_mirror row_mask:0xf bank_mask:0xf bound_ctrl:1
	v_add_f32_e32 v9, v52, v53
	ds_read_b128 v[56:59], v10 offset:20480
	ds_read_b128 v[60:63], v10 offset:20736
	ds_read_b128 v[48:51], v10 offset:19968
	ds_read_b128 v[64:67], v10 offset:20992
	ds_read_b128 v[52:55], v10 offset:20224
	v_add_f32_dpp v80, v80, v80 row_mirror row_mask:0xf bank_mask:0xf bound_ctrl:1
	v_pk_fma_f32 v[4:5], v[80:81], v[84:85], v[76:77] op_sel_hi:[0,1,1]
	v_pk_fma_f32 v[6:7], v[80:81], v[86:87], v[78:79] op_sel_hi:[0,1,1]
	s_waitcnt lgkmcnt(12)
	v_pk_mul_f32 v[116:117], v[4:5], v[116:117]
	v_pk_fma_f32 v[116:117], v[6:7], v[118:119], v[116:117]
	v_add_f32_e32 v116, v116, v117
	v_pk_mul_f32 v[112:113], v[112:113], v[2:3] op_sel:[0,1] op_sel_hi:[1,1]
	v_pk_mul_f32 v[114:115], v[114:115], v[2:3] op_sel:[0,1] op_sel_hi:[1,1]
	v_add_f32_dpp v116, v116, v116 quad_perm:[1,0,3,2] row_mask:0xf bank_mask:0xf bound_ctrl:1
	v_pk_fma_f32 v[112:113], v[4:5], v[104:105], v[112:113]
	v_pk_fma_f32 v[114:115], v[6:7], v[106:107], v[114:115]
	v_add_f32_dpp v116, v116, v116 quad_perm:[2,3,0,1] row_mask:0xf bank_mask:0xf bound_ctrl:1
	v_pk_mul_f32 v[72:73], v[72:73], v[4:5]
	v_pk_fma_f32 v[72:73], v[6:7], v[74:75], v[72:73]
	v_add_f32_dpp v116, v116, v116 row_half_mirror row_mask:0xf bank_mask:0xf bound_ctrl:1
	v_add_f32_e32 v8, v72, v73
	ds_read_b128 v[76:79], v10 offset:22016
	ds_read2st64_b32 v[2:3], v11 offset0:89 offset1:95
	ds_read_b128 v[80:83], v10 offset:22272
	ds_read_b128 v[68:71], v10 offset:21504
	ds_read_b128 v[84:87], v10 offset:22528
	ds_read_b128 v[72:75], v10 offset:21760
	ds_write2st64_b32 v12, v9, v8 offset0:24 offset1:26
	v_add_f32_dpp v116, v116, v116 row_mirror row_mask:0xf bank_mask:0xf bound_ctrl:1
	v_pk_fma_f32 v[4:5], v[116:117], v[120:121], v[112:113] op_sel_hi:[0,1,1]
	v_pk_fma_f32 v[6:7], v[116:117], v[122:123], v[114:115] op_sel_hi:[0,1,1]
	s_waitcnt lgkmcnt(13)
	v_pk_mul_f32 v[40:41], v[4:5], v[40:41]
	v_pk_fma_f32 v[40:41], v[6:7], v[42:43], v[40:41]
	v_add_f32_e32 v40, v40, v41
	v_pk_mul_f32 v[36:37], v[36:37], v[0:1] op_sel_hi:[1,0]
	v_pk_mul_f32 v[38:39], v[38:39], v[0:1] op_sel_hi:[1,0]
	v_add_f32_dpp v40, v40, v40 quad_perm:[1,0,3,2] row_mask:0xf bank_mask:0xf bound_ctrl:1
	v_pk_fma_f32 v[36:37], v[4:5], v[28:29], v[36:37]
	v_pk_fma_f32 v[38:39], v[6:7], v[30:31], v[38:39]
	v_add_f32_dpp v40, v40, v40 quad_perm:[2,3,0,1] row_mask:0xf bank_mask:0xf bound_ctrl:1
	v_pk_mul_f32 v[108:109], v[108:109], v[4:5]
	v_pk_fma_f32 v[108:109], v[6:7], v[110:111], v[108:109]
	v_add_f32_dpp v40, v40, v40 row_half_mirror row_mask:0xf bank_mask:0xf bound_ctrl:1
	v_add_f32_e32 v9, v108, v109
	ds_read_b128 v[112:115], v10 offset:23552
	ds_read_b128 v[116:119], v10 offset:23808
	ds_read_b128 v[104:107], v10 offset:23040
	ds_read_b128 v[120:123], v10 offset:24064
	ds_read_b128 v[108:111], v10 offset:23296
	v_add_f32_dpp v40, v40, v40 row_mirror row_mask:0xf bank_mask:0xf bound_ctrl:1
	v_pk_fma_f32 v[4:5], v[40:41], v[44:45], v[36:37] op_sel_hi:[0,1,1]
	v_pk_fma_f32 v[6:7], v[40:41], v[46:47], v[38:39] op_sel_hi:[0,1,1]
	s_waitcnt lgkmcnt(12)
	v_pk_mul_f32 v[60:61], v[4:5], v[60:61]
	v_pk_fma_f32 v[60:61], v[6:7], v[62:63], v[60:61]
	v_add_f32_e32 v60, v60, v61
	v_pk_mul_f32 v[56:57], v[56:57], v[0:1] op_sel:[0,1] op_sel_hi:[1,1]
	v_pk_mul_f32 v[58:59], v[58:59], v[0:1] op_sel:[0,1] op_sel_hi:[1,1]
	v_add_f32_dpp v60, v60, v60 quad_perm:[1,0,3,2] row_mask:0xf bank_mask:0xf bound_ctrl:1
	v_pk_fma_f32 v[56:57], v[4:5], v[48:49], v[56:57]
	v_pk_fma_f32 v[58:59], v[6:7], v[50:51], v[58:59]
	v_add_f32_dpp v60, v60, v60 quad_perm:[2,3,0,1] row_mask:0xf bank_mask:0xf bound_ctrl:1
	v_pk_mul_f32 v[32:33], v[32:33], v[4:5]
	v_pk_fma_f32 v[32:33], v[6:7], v[34:35], v[32:33]
	v_add_f32_dpp v60, v60, v60 row_half_mirror row_mask:0xf bank_mask:0xf bound_ctrl:1
	v_add_f32_e32 v8, v32, v33
	ds_read_b128 v[36:39], v10 offset:25088
	ds_read2st64_b32 v[0:1], v11 offset0:101 offset1:107
	ds_read_b128 v[40:43], v10 offset:25344
	ds_read_b128 v[28:31], v10 offset:24576
	ds_read_b128 v[44:47], v10 offset:25600
	ds_read_b128 v[32:35], v10 offset:24832
	ds_write2st64_b32 v12, v9, v8 offset0:28 offset1:30
	v_add_f32_dpp v60, v60, v60 row_mirror row_mask:0xf bank_mask:0xf bound_ctrl:1
	v_pk_fma_f32 v[4:5], v[60:61], v[64:65], v[56:57] op_sel_hi:[0,1,1]
	v_pk_fma_f32 v[6:7], v[60:61], v[66:67], v[58:59] op_sel_hi:[0,1,1]
	s_waitcnt lgkmcnt(13)
	v_pk_mul_f32 v[80:81], v[4:5], v[80:81]
	v_pk_fma_f32 v[80:81], v[6:7], v[82:83], v[80:81]
	v_add_f32_e32 v80, v80, v81
	v_pk_mul_f32 v[76:77], v[76:77], v[2:3] op_sel_hi:[1,0]
	v_pk_mul_f32 v[78:79], v[78:79], v[2:3] op_sel_hi:[1,0]
	v_add_f32_dpp v80, v80, v80 quad_perm:[1,0,3,2] row_mask:0xf bank_mask:0xf bound_ctrl:1
	v_pk_fma_f32 v[76:77], v[4:5], v[68:69], v[76:77]
	v_pk_fma_f32 v[78:79], v[6:7], v[70:71], v[78:79]
	v_add_f32_dpp v80, v80, v80 quad_perm:[2,3,0,1] row_mask:0xf bank_mask:0xf bound_ctrl:1
	v_pk_mul_f32 v[52:53], v[52:53], v[4:5]
	v_pk_fma_f32 v[52:53], v[6:7], v[54:55], v[52:53]
	v_add_f32_dpp v80, v80, v80 row_half_mirror row_mask:0xf bank_mask:0xf bound_ctrl:1
	v_add_f32_e32 v9, v52, v53
	ds_read_b128 v[56:59], v10 offset:26624
	ds_read_b128 v[60:63], v10 offset:26880
	ds_read_b128 v[48:51], v10 offset:26112
	ds_read_b128 v[64:67], v10 offset:27136
	ds_read_b128 v[52:55], v10 offset:26368
	v_add_f32_dpp v80, v80, v80 row_mirror row_mask:0xf bank_mask:0xf bound_ctrl:1
	v_pk_fma_f32 v[4:5], v[80:81], v[84:85], v[76:77] op_sel_hi:[0,1,1]
	v_pk_fma_f32 v[6:7], v[80:81], v[86:87], v[78:79] op_sel_hi:[0,1,1]
	s_waitcnt lgkmcnt(12)
	v_pk_mul_f32 v[116:117], v[4:5], v[116:117]
	v_pk_fma_f32 v[116:117], v[6:7], v[118:119], v[116:117]
	v_add_f32_e32 v116, v116, v117
	v_pk_mul_f32 v[112:113], v[112:113], v[2:3] op_sel:[0,1] op_sel_hi:[1,1]
	v_pk_mul_f32 v[114:115], v[114:115], v[2:3] op_sel:[0,1] op_sel_hi:[1,1]
	v_add_f32_dpp v116, v116, v116 quad_perm:[1,0,3,2] row_mask:0xf bank_mask:0xf bound_ctrl:1
	v_pk_fma_f32 v[112:113], v[4:5], v[104:105], v[112:113]
	v_pk_fma_f32 v[114:115], v[6:7], v[106:107], v[114:115]
	v_add_f32_dpp v116, v116, v116 quad_perm:[2,3,0,1] row_mask:0xf bank_mask:0xf bound_ctrl:1
	v_pk_mul_f32 v[72:73], v[72:73], v[4:5]
	v_pk_fma_f32 v[72:73], v[6:7], v[74:75], v[72:73]
	v_add_f32_dpp v116, v116, v116 row_half_mirror row_mask:0xf bank_mask:0xf bound_ctrl:1
	v_add_f32_e32 v8, v72, v73
	ds_read_b128 v[76:79], v10 offset:28160
	ds_read2st64_b32 v[2:3], v11 offset0:113 offset1:119
	ds_read_b128 v[80:83], v10 offset:28416
	ds_read_b128 v[68:71], v10 offset:27648
	ds_read_b128 v[84:87], v10 offset:28672
	ds_read_b128 v[72:75], v10 offset:27904
	ds_write2st64_b32 v12, v9, v8 offset0:32 offset1:34
	v_add_f32_dpp v116, v116, v116 row_mirror row_mask:0xf bank_mask:0xf bound_ctrl:1
	v_pk_fma_f32 v[4:5], v[116:117], v[120:121], v[112:113] op_sel_hi:[0,1,1]
	v_pk_fma_f32 v[6:7], v[116:117], v[122:123], v[114:115] op_sel_hi:[0,1,1]
	s_waitcnt lgkmcnt(13)
	v_pk_mul_f32 v[40:41], v[4:5], v[40:41]
	v_pk_fma_f32 v[40:41], v[6:7], v[42:43], v[40:41]
	v_add_f32_e32 v40, v40, v41
	v_pk_mul_f32 v[36:37], v[36:37], v[0:1] op_sel_hi:[1,0]
	v_pk_mul_f32 v[38:39], v[38:39], v[0:1] op_sel_hi:[1,0]
	v_add_f32_dpp v40, v40, v40 quad_perm:[1,0,3,2] row_mask:0xf bank_mask:0xf bound_ctrl:1
	v_pk_fma_f32 v[36:37], v[4:5], v[28:29], v[36:37]
	v_pk_fma_f32 v[38:39], v[6:7], v[30:31], v[38:39]
	v_add_f32_dpp v40, v40, v40 quad_perm:[2,3,0,1] row_mask:0xf bank_mask:0xf bound_ctrl:1
	v_pk_mul_f32 v[108:109], v[108:109], v[4:5]
	v_pk_fma_f32 v[108:109], v[6:7], v[110:111], v[108:109]
	v_add_f32_dpp v40, v40, v40 row_half_mirror row_mask:0xf bank_mask:0xf bound_ctrl:1
	v_add_f32_e32 v9, v108, v109
	ds_read_b128 v[112:115], v10 offset:29696
	ds_read_b128 v[116:119], v10 offset:29952
	ds_read_b128 v[104:107], v10 offset:29184
	ds_read_b128 v[120:123], v10 offset:30208
	ds_read_b128 v[108:111], v10 offset:29440
	v_add_f32_dpp v40, v40, v40 row_mirror row_mask:0xf bank_mask:0xf bound_ctrl:1
	v_pk_fma_f32 v[4:5], v[40:41], v[44:45], v[36:37] op_sel_hi:[0,1,1]
	v_pk_fma_f32 v[6:7], v[40:41], v[46:47], v[38:39] op_sel_hi:[0,1,1]
	s_waitcnt lgkmcnt(12)
	v_pk_mul_f32 v[60:61], v[4:5], v[60:61]
	v_pk_fma_f32 v[60:61], v[6:7], v[62:63], v[60:61]
	v_add_f32_e32 v60, v60, v61
	v_pk_mul_f32 v[56:57], v[56:57], v[0:1] op_sel:[0,1] op_sel_hi:[1,1]
	v_pk_mul_f32 v[58:59], v[58:59], v[0:1] op_sel:[0,1] op_sel_hi:[1,1]
	v_add_f32_dpp v60, v60, v60 quad_perm:[1,0,3,2] row_mask:0xf bank_mask:0xf bound_ctrl:1
	v_pk_fma_f32 v[56:57], v[4:5], v[48:49], v[56:57]
	v_pk_fma_f32 v[58:59], v[6:7], v[50:51], v[58:59]
	v_add_f32_dpp v60, v60, v60 quad_perm:[2,3,0,1] row_mask:0xf bank_mask:0xf bound_ctrl:1
	v_pk_mul_f32 v[32:33], v[32:33], v[4:5]
	v_pk_fma_f32 v[32:33], v[6:7], v[34:35], v[32:33]
	v_add_f32_dpp v60, v60, v60 row_half_mirror row_mask:0xf bank_mask:0xf bound_ctrl:1
	v_add_f32_e32 v8, v32, v33
	ds_read_b128 v[36:39], v10 offset:31232
	ds_read2st64_b32 v[0:1], v11 offset0:125 offset1:131
	ds_read_b128 v[40:43], v10 offset:31488
	ds_read_b128 v[28:31], v10 offset:30720
	ds_read_b128 v[44:47], v10 offset:31744
	ds_read_b128 v[32:35], v10 offset:30976
	ds_write2st64_b32 v12, v9, v8 offset0:36 offset1:38
	v_add_f32_dpp v60, v60, v60 row_mirror row_mask:0xf bank_mask:0xf bound_ctrl:1
	v_pk_fma_f32 v[4:5], v[60:61], v[64:65], v[56:57] op_sel_hi:[0,1,1]
	v_pk_fma_f32 v[6:7], v[60:61], v[66:67], v[58:59] op_sel_hi:[0,1,1]
	s_waitcnt lgkmcnt(13)
	v_pk_mul_f32 v[80:81], v[4:5], v[80:81]
	v_pk_fma_f32 v[80:81], v[6:7], v[82:83], v[80:81]
	v_add_f32_e32 v80, v80, v81
	v_pk_mul_f32 v[76:77], v[76:77], v[2:3] op_sel_hi:[1,0]
	v_pk_mul_f32 v[78:79], v[78:79], v[2:3] op_sel_hi:[1,0]
	v_add_f32_dpp v80, v80, v80 quad_perm:[1,0,3,2] row_mask:0xf bank_mask:0xf bound_ctrl:1
	v_pk_fma_f32 v[76:77], v[4:5], v[68:69], v[76:77]
	v_pk_fma_f32 v[78:79], v[6:7], v[70:71], v[78:79]
	v_add_f32_dpp v80, v80, v80 quad_perm:[2,3,0,1] row_mask:0xf bank_mask:0xf bound_ctrl:1
	v_pk_mul_f32 v[52:53], v[52:53], v[4:5]
	v_pk_fma_f32 v[52:53], v[6:7], v[54:55], v[52:53]
	v_add_f32_dpp v80, v80, v80 row_half_mirror row_mask:0xf bank_mask:0xf bound_ctrl:1
	v_add_f32_e32 v9, v52, v53
	ds_read_b128 v[56:59], v10 offset:32768
	ds_read_b128 v[60:63], v10 offset:33024
	ds_read_b128 v[48:51], v10 offset:32256
	ds_read_b128 v[64:67], v10 offset:33280
	ds_read_b128 v[52:55], v10 offset:32512
	v_add_f32_dpp v80, v80, v80 row_mirror row_mask:0xf bank_mask:0xf bound_ctrl:1
	v_pk_fma_f32 v[4:5], v[80:81], v[84:85], v[76:77] op_sel_hi:[0,1,1]
	v_pk_fma_f32 v[6:7], v[80:81], v[86:87], v[78:79] op_sel_hi:[0,1,1]
	s_waitcnt lgkmcnt(12)
	v_pk_mul_f32 v[116:117], v[4:5], v[116:117]
	v_pk_fma_f32 v[116:117], v[6:7], v[118:119], v[116:117]
	v_add_f32_e32 v116, v116, v117
	v_pk_mul_f32 v[112:113], v[112:113], v[2:3] op_sel:[0,1] op_sel_hi:[1,1]
	v_pk_mul_f32 v[114:115], v[114:115], v[2:3] op_sel:[0,1] op_sel_hi:[1,1]
	v_add_f32_dpp v116, v116, v116 quad_perm:[1,0,3,2] row_mask:0xf bank_mask:0xf bound_ctrl:1
	v_pk_fma_f32 v[112:113], v[4:5], v[104:105], v[112:113]
	v_pk_fma_f32 v[114:115], v[6:7], v[106:107], v[114:115]
	v_add_f32_dpp v116, v116, v116 quad_perm:[2,3,0,1] row_mask:0xf bank_mask:0xf bound_ctrl:1
	v_pk_mul_f32 v[72:73], v[72:73], v[4:5]
	v_pk_fma_f32 v[72:73], v[6:7], v[74:75], v[72:73]
	v_add_f32_dpp v116, v116, v116 row_half_mirror row_mask:0xf bank_mask:0xf bound_ctrl:1
	v_add_f32_e32 v8, v72, v73
	ds_read_b128 v[76:79], v10 offset:34304
	ds_read2st64_b32 v[2:3], v11 offset0:137 offset1:143
	ds_read_b128 v[80:83], v10 offset:34560
	ds_read_b128 v[68:71], v10 offset:33792
	ds_read_b128 v[84:87], v10 offset:34816
	ds_read_b128 v[72:75], v10 offset:34048
	ds_write2st64_b32 v12, v9, v8 offset0:40 offset1:42
	v_add_f32_dpp v116, v116, v116 row_mirror row_mask:0xf bank_mask:0xf bound_ctrl:1
	v_pk_fma_f32 v[4:5], v[116:117], v[120:121], v[112:113] op_sel_hi:[0,1,1]
	v_pk_fma_f32 v[6:7], v[116:117], v[122:123], v[114:115] op_sel_hi:[0,1,1]
	s_waitcnt lgkmcnt(13)
	v_pk_mul_f32 v[40:41], v[4:5], v[40:41]
	v_pk_fma_f32 v[40:41], v[6:7], v[42:43], v[40:41]
	v_add_f32_e32 v40, v40, v41
	v_pk_mul_f32 v[36:37], v[36:37], v[0:1] op_sel_hi:[1,0]
	v_pk_mul_f32 v[38:39], v[38:39], v[0:1] op_sel_hi:[1,0]
	v_add_f32_dpp v40, v40, v40 quad_perm:[1,0,3,2] row_mask:0xf bank_mask:0xf bound_ctrl:1
	v_pk_fma_f32 v[36:37], v[4:5], v[28:29], v[36:37]
	v_pk_fma_f32 v[38:39], v[6:7], v[30:31], v[38:39]
	v_add_f32_dpp v40, v40, v40 quad_perm:[2,3,0,1] row_mask:0xf bank_mask:0xf bound_ctrl:1
	v_pk_mul_f32 v[108:109], v[108:109], v[4:5]
	v_pk_fma_f32 v[108:109], v[6:7], v[110:111], v[108:109]
	v_add_f32_dpp v40, v40, v40 row_half_mirror row_mask:0xf bank_mask:0xf bound_ctrl:1
	v_add_f32_e32 v9, v108, v109
	ds_read_b128 v[112:115], v10 offset:35840
	ds_read_b128 v[116:119], v10 offset:36096
	ds_read_b128 v[104:107], v10 offset:35328
	ds_read_b128 v[120:123], v10 offset:36352
	ds_read_b128 v[108:111], v10 offset:35584
	v_add_f32_dpp v40, v40, v40 row_mirror row_mask:0xf bank_mask:0xf bound_ctrl:1
	v_pk_fma_f32 v[4:5], v[40:41], v[44:45], v[36:37] op_sel_hi:[0,1,1]
	v_pk_fma_f32 v[6:7], v[40:41], v[46:47], v[38:39] op_sel_hi:[0,1,1]
	s_waitcnt lgkmcnt(12)
	v_pk_mul_f32 v[60:61], v[4:5], v[60:61]
	v_pk_fma_f32 v[60:61], v[6:7], v[62:63], v[60:61]
	v_add_f32_e32 v60, v60, v61
	v_pk_mul_f32 v[56:57], v[56:57], v[0:1] op_sel:[0,1] op_sel_hi:[1,1]
	v_pk_mul_f32 v[58:59], v[58:59], v[0:1] op_sel:[0,1] op_sel_hi:[1,1]
	v_add_f32_dpp v60, v60, v60 quad_perm:[1,0,3,2] row_mask:0xf bank_mask:0xf bound_ctrl:1
	v_pk_fma_f32 v[56:57], v[4:5], v[48:49], v[56:57]
	v_pk_fma_f32 v[58:59], v[6:7], v[50:51], v[58:59]
	v_add_f32_dpp v60, v60, v60 quad_perm:[2,3,0,1] row_mask:0xf bank_mask:0xf bound_ctrl:1
	v_pk_mul_f32 v[32:33], v[32:33], v[4:5]
	v_pk_fma_f32 v[32:33], v[6:7], v[34:35], v[32:33]
	v_add_f32_dpp v60, v60, v60 row_half_mirror row_mask:0xf bank_mask:0xf bound_ctrl:1
	v_add_f32_e32 v8, v32, v33
	ds_read_b128 v[36:39], v10 offset:37376
	ds_read2st64_b32 v[0:1], v11 offset0:149 offset1:155
	ds_read_b128 v[40:43], v10 offset:37632
	ds_read_b128 v[28:31], v10 offset:36864
	ds_read_b128 v[44:47], v10 offset:37888
	ds_read_b128 v[32:35], v10 offset:37120
	ds_write2st64_b32 v12, v9, v8 offset0:44 offset1:46
	v_add_f32_dpp v60, v60, v60 row_mirror row_mask:0xf bank_mask:0xf bound_ctrl:1
	v_pk_fma_f32 v[4:5], v[60:61], v[64:65], v[56:57] op_sel_hi:[0,1,1]
	v_pk_fma_f32 v[6:7], v[60:61], v[66:67], v[58:59] op_sel_hi:[0,1,1]
	s_waitcnt lgkmcnt(13)
	v_pk_mul_f32 v[80:81], v[4:5], v[80:81]
	v_pk_fma_f32 v[80:81], v[6:7], v[82:83], v[80:81]
	v_add_f32_e32 v80, v80, v81
	v_pk_mul_f32 v[76:77], v[76:77], v[2:3] op_sel_hi:[1,0]
	v_pk_mul_f32 v[78:79], v[78:79], v[2:3] op_sel_hi:[1,0]
	v_add_f32_dpp v80, v80, v80 quad_perm:[1,0,3,2] row_mask:0xf bank_mask:0xf bound_ctrl:1
	v_pk_fma_f32 v[76:77], v[4:5], v[68:69], v[76:77]
	v_pk_fma_f32 v[78:79], v[6:7], v[70:71], v[78:79]
	v_add_f32_dpp v80, v80, v80 quad_perm:[2,3,0,1] row_mask:0xf bank_mask:0xf bound_ctrl:1
	v_pk_mul_f32 v[52:53], v[52:53], v[4:5]
	v_pk_fma_f32 v[52:53], v[6:7], v[54:55], v[52:53]
	v_add_f32_dpp v80, v80, v80 row_half_mirror row_mask:0xf bank_mask:0xf bound_ctrl:1
	v_add_f32_e32 v9, v52, v53
	ds_read_b128 v[56:59], v10 offset:38912
	ds_read_b128 v[60:63], v10 offset:39168
	ds_read_b128 v[48:51], v10 offset:38400
	ds_read_b128 v[64:67], v10 offset:39424
	ds_read_b128 v[52:55], v10 offset:38656
	v_add_f32_dpp v80, v80, v80 row_mirror row_mask:0xf bank_mask:0xf bound_ctrl:1
	v_pk_fma_f32 v[4:5], v[80:81], v[84:85], v[76:77] op_sel_hi:[0,1,1]
	v_pk_fma_f32 v[6:7], v[80:81], v[86:87], v[78:79] op_sel_hi:[0,1,1]
	s_waitcnt lgkmcnt(12)
	v_pk_mul_f32 v[116:117], v[4:5], v[116:117]
	v_pk_fma_f32 v[116:117], v[6:7], v[118:119], v[116:117]
	v_add_f32_e32 v116, v116, v117
	v_pk_mul_f32 v[112:113], v[112:113], v[2:3] op_sel:[0,1] op_sel_hi:[1,1]
	v_pk_mul_f32 v[114:115], v[114:115], v[2:3] op_sel:[0,1] op_sel_hi:[1,1]
	v_add_f32_dpp v116, v116, v116 quad_perm:[1,0,3,2] row_mask:0xf bank_mask:0xf bound_ctrl:1
	v_pk_fma_f32 v[112:113], v[4:5], v[104:105], v[112:113]
	v_pk_fma_f32 v[114:115], v[6:7], v[106:107], v[114:115]
	v_add_f32_dpp v116, v116, v116 quad_perm:[2,3,0,1] row_mask:0xf bank_mask:0xf bound_ctrl:1
	v_pk_mul_f32 v[72:73], v[72:73], v[4:5]
	v_pk_fma_f32 v[72:73], v[6:7], v[74:75], v[72:73]
	v_add_f32_dpp v116, v116, v116 row_half_mirror row_mask:0xf bank_mask:0xf bound_ctrl:1
	v_add_f32_e32 v8, v72, v73
	ds_read_b128 v[76:79], v10 offset:40448
	ds_read2st64_b32 v[2:3], v11 offset0:161 offset1:167
	ds_read_b128 v[80:83], v10 offset:40704
	ds_read_b128 v[68:71], v10 offset:39936
	ds_read_b128 v[84:87], v10 offset:40960
	ds_read_b128 v[72:75], v10 offset:40192
	ds_write2st64_b32 v12, v9, v8 offset0:48 offset1:50
	v_add_f32_dpp v116, v116, v116 row_mirror row_mask:0xf bank_mask:0xf bound_ctrl:1
	v_pk_fma_f32 v[4:5], v[116:117], v[120:121], v[112:113] op_sel_hi:[0,1,1]
	v_pk_fma_f32 v[6:7], v[116:117], v[122:123], v[114:115] op_sel_hi:[0,1,1]
	s_waitcnt lgkmcnt(13)
	v_pk_mul_f32 v[40:41], v[4:5], v[40:41]
	v_pk_fma_f32 v[40:41], v[6:7], v[42:43], v[40:41]
	v_add_f32_e32 v40, v40, v41
	v_pk_mul_f32 v[36:37], v[36:37], v[0:1] op_sel_hi:[1,0]
	v_pk_mul_f32 v[38:39], v[38:39], v[0:1] op_sel_hi:[1,0]
	v_add_f32_dpp v40, v40, v40 quad_perm:[1,0,3,2] row_mask:0xf bank_mask:0xf bound_ctrl:1
	v_pk_fma_f32 v[36:37], v[4:5], v[28:29], v[36:37]
	v_pk_fma_f32 v[38:39], v[6:7], v[30:31], v[38:39]
	v_add_f32_dpp v40, v40, v40 quad_perm:[2,3,0,1] row_mask:0xf bank_mask:0xf bound_ctrl:1
	v_pk_mul_f32 v[108:109], v[108:109], v[4:5]
	v_pk_fma_f32 v[108:109], v[6:7], v[110:111], v[108:109]
	v_add_f32_dpp v40, v40, v40 row_half_mirror row_mask:0xf bank_mask:0xf bound_ctrl:1
	v_add_f32_e32 v9, v108, v109
	ds_read_b128 v[112:115], v10 offset:41984
	ds_read_b128 v[116:119], v10 offset:42240
	ds_read_b128 v[104:107], v10 offset:41472
	ds_read_b128 v[120:123], v10 offset:42496
	ds_read_b128 v[108:111], v10 offset:41728
	v_add_f32_dpp v40, v40, v40 row_mirror row_mask:0xf bank_mask:0xf bound_ctrl:1
	v_pk_fma_f32 v[4:5], v[40:41], v[44:45], v[36:37] op_sel_hi:[0,1,1]
	v_pk_fma_f32 v[6:7], v[40:41], v[46:47], v[38:39] op_sel_hi:[0,1,1]
	s_waitcnt lgkmcnt(12)
	v_pk_mul_f32 v[60:61], v[4:5], v[60:61]
	v_pk_fma_f32 v[60:61], v[6:7], v[62:63], v[60:61]
	v_add_f32_e32 v60, v60, v61
	v_pk_mul_f32 v[56:57], v[56:57], v[0:1] op_sel:[0,1] op_sel_hi:[1,1]
	v_pk_mul_f32 v[58:59], v[58:59], v[0:1] op_sel:[0,1] op_sel_hi:[1,1]
	v_add_f32_dpp v60, v60, v60 quad_perm:[1,0,3,2] row_mask:0xf bank_mask:0xf bound_ctrl:1
	v_pk_fma_f32 v[56:57], v[4:5], v[48:49], v[56:57]
	v_pk_fma_f32 v[58:59], v[6:7], v[50:51], v[58:59]
	v_add_f32_dpp v60, v60, v60 quad_perm:[2,3,0,1] row_mask:0xf bank_mask:0xf bound_ctrl:1
	v_pk_mul_f32 v[32:33], v[32:33], v[4:5]
	v_pk_fma_f32 v[32:33], v[6:7], v[34:35], v[32:33]
	v_add_f32_dpp v60, v60, v60 row_half_mirror row_mask:0xf bank_mask:0xf bound_ctrl:1
	v_add_f32_e32 v8, v32, v33
	ds_read_b128 v[36:39], v10 offset:43520
	ds_read2st64_b32 v[0:1], v11 offset0:173 offset1:179
	ds_read_b128 v[40:43], v10 offset:43776
	ds_read_b128 v[28:31], v10 offset:43008
	ds_read_b128 v[44:47], v10 offset:44032
	ds_read_b128 v[32:35], v10 offset:43264
	ds_write2st64_b32 v12, v9, v8 offset0:52 offset1:54
	v_add_f32_dpp v60, v60, v60 row_mirror row_mask:0xf bank_mask:0xf bound_ctrl:1
	v_pk_fma_f32 v[4:5], v[60:61], v[64:65], v[56:57] op_sel_hi:[0,1,1]
	v_pk_fma_f32 v[6:7], v[60:61], v[66:67], v[58:59] op_sel_hi:[0,1,1]
	s_waitcnt lgkmcnt(13)
	v_pk_mul_f32 v[80:81], v[4:5], v[80:81]
	v_pk_fma_f32 v[80:81], v[6:7], v[82:83], v[80:81]
	v_add_f32_e32 v80, v80, v81
	v_pk_mul_f32 v[76:77], v[76:77], v[2:3] op_sel_hi:[1,0]
	v_pk_mul_f32 v[78:79], v[78:79], v[2:3] op_sel_hi:[1,0]
	v_add_f32_dpp v80, v80, v80 quad_perm:[1,0,3,2] row_mask:0xf bank_mask:0xf bound_ctrl:1
	v_pk_fma_f32 v[76:77], v[4:5], v[68:69], v[76:77]
	v_pk_fma_f32 v[78:79], v[6:7], v[70:71], v[78:79]
	v_add_f32_dpp v80, v80, v80 quad_perm:[2,3,0,1] row_mask:0xf bank_mask:0xf bound_ctrl:1
	v_pk_mul_f32 v[52:53], v[52:53], v[4:5]
	v_pk_fma_f32 v[52:53], v[6:7], v[54:55], v[52:53]
	v_add_f32_dpp v80, v80, v80 row_half_mirror row_mask:0xf bank_mask:0xf bound_ctrl:1
	v_add_f32_e32 v9, v52, v53
	ds_read_b128 v[56:59], v10 offset:45056
	ds_read_b128 v[60:63], v10 offset:45312
	ds_read_b128 v[48:51], v10 offset:44544
	ds_read_b128 v[64:67], v10 offset:45568
	ds_read_b128 v[52:55], v10 offset:44800
	v_add_f32_dpp v80, v80, v80 row_mirror row_mask:0xf bank_mask:0xf bound_ctrl:1
	v_pk_fma_f32 v[4:5], v[80:81], v[84:85], v[76:77] op_sel_hi:[0,1,1]
	v_pk_fma_f32 v[6:7], v[80:81], v[86:87], v[78:79] op_sel_hi:[0,1,1]
	s_waitcnt lgkmcnt(12)
	v_pk_mul_f32 v[116:117], v[4:5], v[116:117]
	v_pk_fma_f32 v[116:117], v[6:7], v[118:119], v[116:117]
	v_add_f32_e32 v116, v116, v117
	v_pk_mul_f32 v[112:113], v[112:113], v[2:3] op_sel:[0,1] op_sel_hi:[1,1]
	v_pk_mul_f32 v[114:115], v[114:115], v[2:3] op_sel:[0,1] op_sel_hi:[1,1]
	v_add_f32_dpp v116, v116, v116 quad_perm:[1,0,3,2] row_mask:0xf bank_mask:0xf bound_ctrl:1
	v_pk_fma_f32 v[112:113], v[4:5], v[104:105], v[112:113]
	v_pk_fma_f32 v[114:115], v[6:7], v[106:107], v[114:115]
	v_add_f32_dpp v116, v116, v116 quad_perm:[2,3,0,1] row_mask:0xf bank_mask:0xf bound_ctrl:1
	v_pk_mul_f32 v[72:73], v[72:73], v[4:5]
	v_pk_fma_f32 v[72:73], v[6:7], v[74:75], v[72:73]
	v_add_f32_dpp v116, v116, v116 row_half_mirror row_mask:0xf bank_mask:0xf bound_ctrl:1
	v_add_f32_e32 v8, v72, v73
	ds_read_b128 v[76:79], v10 offset:46592
	ds_read2st64_b32 v[2:3], v11 offset0:185 offset1:191
	ds_read_b128 v[80:83], v10 offset:46848
	ds_read_b128 v[68:71], v10 offset:46080
	ds_read_b128 v[84:87], v10 offset:47104
	ds_read_b128 v[72:75], v10 offset:46336
	ds_write2st64_b32 v12, v9, v8 offset0:56 offset1:58
	v_add_f32_dpp v116, v116, v116 row_mirror row_mask:0xf bank_mask:0xf bound_ctrl:1
	v_pk_fma_f32 v[4:5], v[116:117], v[120:121], v[112:113] op_sel_hi:[0,1,1]
	v_pk_fma_f32 v[6:7], v[116:117], v[122:123], v[114:115] op_sel_hi:[0,1,1]
	s_waitcnt lgkmcnt(13)
	v_pk_mul_f32 v[40:41], v[4:5], v[40:41]
	v_pk_fma_f32 v[40:41], v[6:7], v[42:43], v[40:41]
	v_add_f32_e32 v40, v40, v41
	v_pk_mul_f32 v[36:37], v[36:37], v[0:1] op_sel_hi:[1,0]
	v_pk_mul_f32 v[38:39], v[38:39], v[0:1] op_sel_hi:[1,0]
	v_add_f32_dpp v40, v40, v40 quad_perm:[1,0,3,2] row_mask:0xf bank_mask:0xf bound_ctrl:1
	v_pk_fma_f32 v[36:37], v[4:5], v[28:29], v[36:37]
	v_pk_fma_f32 v[38:39], v[6:7], v[30:31], v[38:39]
	v_add_f32_dpp v40, v40, v40 quad_perm:[2,3,0,1] row_mask:0xf bank_mask:0xf bound_ctrl:1
	v_pk_mul_f32 v[108:109], v[108:109], v[4:5]
	v_pk_fma_f32 v[108:109], v[6:7], v[110:111], v[108:109]
	v_add_f32_dpp v40, v40, v40 row_half_mirror row_mask:0xf bank_mask:0xf bound_ctrl:1
	v_add_f32_e32 v9, v108, v109
	ds_read_b128 v[112:115], v10 offset:48128
	ds_read_b128 v[116:119], v10 offset:48384
	ds_read_b128 v[104:107], v10 offset:47616
	ds_read_b128 v[120:123], v10 offset:48640
	ds_read_b128 v[108:111], v10 offset:47872
	v_add_f32_dpp v40, v40, v40 row_mirror row_mask:0xf bank_mask:0xf bound_ctrl:1
	v_pk_fma_f32 v[4:5], v[40:41], v[44:45], v[36:37] op_sel_hi:[0,1,1]
	v_pk_fma_f32 v[6:7], v[40:41], v[46:47], v[38:39] op_sel_hi:[0,1,1]
	s_waitcnt lgkmcnt(12)
	v_pk_mul_f32 v[60:61], v[4:5], v[60:61]
	v_pk_fma_f32 v[60:61], v[6:7], v[62:63], v[60:61]
	v_add_f32_e32 v60, v60, v61
	v_pk_mul_f32 v[56:57], v[56:57], v[0:1] op_sel:[0,1] op_sel_hi:[1,1]
	v_pk_mul_f32 v[58:59], v[58:59], v[0:1] op_sel:[0,1] op_sel_hi:[1,1]
	v_add_f32_dpp v60, v60, v60 quad_perm:[1,0,3,2] row_mask:0xf bank_mask:0xf bound_ctrl:1
	v_pk_fma_f32 v[56:57], v[4:5], v[48:49], v[56:57]
	v_pk_fma_f32 v[58:59], v[6:7], v[50:51], v[58:59]
	v_add_f32_dpp v60, v60, v60 quad_perm:[2,3,0,1] row_mask:0xf bank_mask:0xf bound_ctrl:1
	v_pk_mul_f32 v[32:33], v[32:33], v[4:5]
	v_pk_fma_f32 v[32:33], v[6:7], v[34:35], v[32:33]
	v_add_f32_dpp v60, v60, v60 row_half_mirror row_mask:0xf bank_mask:0xf bound_ctrl:1
	v_add_f32_e32 v8, v32, v33
	ds_write2st64_b32 v12, v9, v8 offset0:60 offset1:62
	s_nop 0
	v_add_f32_dpp v60, v60, v60 row_mirror row_mask:0xf bank_mask:0xf bound_ctrl:1
